# FFN gate/up chained tiles: rstd loads issued before the next-tile LDS-DMA prefetch, counted vmcnt(8) waits so the prefetch stays in flight under the epilogue
# baseline (speedup 1.0000x reference)
; DI float fexp2(float x) { return __builtin_amdgcn_exp2f(x); }
;     ...
;   if constexpr (EPI == EPI_GU) {
;     __syncthreads();
;     const float* rstdL = (const float*)(smem + SMEM_RSTD);
; #pragma unroll
;     for (int ai = 0; ai < 2; ++ai)
; #pragma unroll
;       for (int m = 0; m < 4; ++m) {
;         const int rowb = ai * 128 + wr * 64 + m * 16 + fq * 4;
;         const f32x4 rs4 = *(const f32x4*)(rstdL + rowb);
; #pragma unroll
;         for (int bj = 0; bj < 2; ++bj) {
;           bf16_t* op = e.out + (size_t)(m0 + rowb) * e.ldo + ((n0 + bj * 128 + wc * 32) >> 1) + fr;
; #pragma unroll
;           for (int j = 0; j < 4; ++j) {
;             const float g = acc[ai][bj][m][0][j] * rs4[j], u = acc[ai][bj][m][1][j] * rs4[j];
;             const float rv = g * __builtin_amdgcn_rcpf(1.f + fexp2(-g * LOG2E)) * u;
;             op[(size_t)j * e.ldo] = (bf16_t)(pack2(rv, 0.f) & 0xffffu);
;           }
;         }
;       }
.LBB0_1243:
	s_or_b64 exec, exec, s[2:3]
	v_lshl_or_b32 v135, v148, 2, v149
	v_mov_b32_e32 v144, 0x21010
	v_lshl_add_u32 v134, v135, 2, v144
	s_waitcnt vmcnt(8) lgkmcnt(0)
	s_barrier
	ds_read_b128 v[136:139], v134
	v_lshl_or_b32 v132, v146, 5, s0
	v_lshlrev_b32_e32 v0, 1, v147
	v_mov_b32_e32 v1, v2
	v_ashrrev_i32_e32 v132, 1, v132
	s_waitcnt lgkmcnt(0)
	v_mul_f32_e32 v128, v128, v136
	v_mul_f32_e32 v133, 0xbfb8aa3b, v128
	v_exp_f32_e32 v142, v133
	v_mul_f32_e32 v129, v129, v137
	v_mul_f32_e32 v143, 0xbfb8aa3b, v129
	v_exp_f32_e32 v143, v143
	v_add_f32_e32 v142, 1.0, v142
	v_rcp_f32_e32 v142, v142
	v_mul_f32_e32 v124, v124, v136
	v_lshl_add_u64 v[0:1], s[30:31], 0, v[0:1]
	v_add_u32_e32 v3, s27, v135
	v_mul_f32_e32 v128, v128, v142
	v_mul_f32_e32 v124, v124, v128
	v_add_f32_e32 v128, 1.0, v143
	v_rcp_f32_e32 v128, v128
	s_movk_i32 s13, 0x1600
	v_ashrrev_i32_e32 v133, 31, v132
	v_mad_i64_i32 v[140:141], s[0:1], v3, s13, v[0:1]
	v_lshlrev_b64 v[132:133], 1, v[132:133]
	v_lshl_add_u64 v[140:141], v[140:141], 0, v[132:133]
	v_cvt_pk_bf16_f32 v124, v124, s0
	global_store_short v[140:141], v124, off
	v_mul_f32_e32 v124, v125, v137
	v_mul_f32_e32 v125, v129, v128
	v_mul_f32_e32 v128, v130, v138
	v_mul_f32_e32 v124, v124, v125
	v_mul_f32_e32 v125, 0xbfb8aa3b, v128
	v_exp_f32_e32 v125, v125
	s_movk_i32 s12, 0x1000
	v_cvt_pk_bf16_f32 v129, v124, s0
	v_add_co_u32_e32 v124, vcc, s12, v140
	v_add_f32_e32 v125, 1.0, v125
	v_rcp_f32_e32 v130, v125
	v_mul_f32_e32 v126, v126, v138
	v_addc_co_u32_e32 v125, vcc, 0, v141, vcc
	v_mul_f32_e32 v128, v128, v130
	v_mul_f32_e32 v130, v131, v139
	v_mul_f32_e32 v126, v126, v128
	v_mul_f32_e32 v128, 0xbfb8aa3b, v130
	global_store_short v[124:125], v129, off offset:1536
	v_exp_f32_e32 v129, v128
	s_movk_i32 s2, 0x2000
	v_add_co_u32_e32 v128, vcc, s2, v140
	v_add_f32_e32 v129, 1.0, v129
	v_rcp_f32_e32 v131, v129
	v_cvt_pk_bf16_f32 v126, v126, s0
	v_addc_co_u32_e32 v129, vcc, 0, v141, vcc
	global_store_short v[128:129], v126, off offset:3072
	v_mul_f32_e32 v126, v127, v139
	v_mul_f32_e32 v127, v130, v131
	v_mul_f32_e32 v120, v120, v136
	v_mul_f32_e32 v126, v126, v127
	v_mul_f32_e32 v127, 0xbfb8aa3b, v120
	v_exp_f32_e32 v131, v127
	s_movk_i32 s3, 0x4000
	v_cvt_pk_bf16_f32 v130, v126, s0
	v_add_co_u32_e32 v126, vcc, s3, v140
	v_mul_f32_e32 v121, v121, v137
	s_nop 0
	v_addc_co_u32_e32 v127, vcc, 0, v141, vcc
	global_store_short v[126:127], v130, off offset:512
	v_add_f32_e32 v130, 1.0, v131
	v_rcp_f32_e32 v130, v130
	v_mul_f32_e32 v131, 0xbfb8aa3b, v121
	v_exp_f32_e32 v131, v131
	v_mul_f32_e32 v116, v116, v136
	v_mul_f32_e32 v120, v120, v130
	v_mul_f32_e32 v116, v116, v120
	v_add_f32_e32 v120, 1.0, v131
	v_rcp_f32_e32 v120, v120
	v_cvt_pk_bf16_f32 v116, v116, s0
	global_store_short v[140:141], v116, off offset:128
	v_mul_f32_e32 v116, v117, v137
	v_mul_f32_e32 v117, v121, v120
	v_mul_f32_e32 v120, v122, v138
	v_mul_f32_e32 v121, 0xbfb8aa3b, v120
	v_exp_f32_e32 v121, v121
	v_mul_f32_e32 v116, v116, v117
	v_cvt_pk_bf16_f32 v116, v116, s0
	global_store_short v[124:125], v116, off offset:1664
	v_add_f32_e32 v116, 1.0, v121
	v_mul_f32_e32 v117, v123, v139
	v_rcp_f32_e32 v116, v116
	v_mul_f32_e32 v121, 0xbfb8aa3b, v117
	v_exp_f32_e32 v121, v121
	v_mul_f32_e32 v118, v118, v138
	v_mul_f32_e32 v116, v120, v116
	v_mul_f32_e32 v116, v118, v116
	v_add_f32_e32 v118, 1.0, v121
	v_rcp_f32_e32 v118, v118
	v_cvt_pk_bf16_f32 v116, v116, s0
	v_or_b32_e32 v122, 16, v135
	global_store_short v[128:129], v116, off offset:3200
	v_lshl_add_u32 v116, v122, 2, v144
	v_mul_f32_e32 v120, v119, v139
	v_mul_f32_e32 v121, v117, v118
	ds_read_b128 v[116:119], v116
	v_mul_f32_e32 v120, v120, v121
	v_cvt_pk_bf16_f32 v120, v120, s0
	global_store_short v[126:127], v120, off offset:640
	v_add_u32_e32 v120, s27, v122
	s_waitcnt lgkmcnt(0)
	v_mul_f32_e32 v112, v112, v116
	v_mul_f32_e32 v121, 0xbfb8aa3b, v112
	v_exp_f32_e32 v122, v121
	v_mul_f32_e32 v113, v113, v117
	v_mul_f32_e32 v123, 0xbfb8aa3b, v113
	v_exp_f32_e32 v123, v123
	v_add_f32_e32 v122, 1.0, v122
	v_rcp_f32_e32 v122, v122
	v_mul_f32_e32 v108, v108, v116
	v_mad_i64_i32 v[120:121], s[0:1], v120, s13, v[0:1]
	v_mul_f32_e32 v112, v112, v122
	v_mul_f32_e32 v108, v108, v112
	v_add_f32_e32 v112, 1.0, v123
	v_rcp_f32_e32 v112, v112
	v_lshl_add_u64 v[120:121], v[120:121], 0, v[132:133]
	v_cvt_pk_bf16_f32 v108, v108, s0
	global_store_short v[120:121], v108, off
	v_mul_f32_e32 v108, v109, v117
	v_mul_f32_e32 v109, v113, v112
	v_mul_f32_e32 v112, v114, v118
	v_mul_f32_e32 v108, v108, v109
	v_mul_f32_e32 v109, 0xbfb8aa3b, v112
	v_exp_f32_e32 v109, v109
	v_cvt_pk_bf16_f32 v113, v108, s0
	v_add_co_u32_e32 v108, vcc, s12, v120
	v_add_f32_e32 v109, 1.0, v109
	v_rcp_f32_e32 v114, v109
	v_mul_f32_e32 v110, v110, v118
	v_addc_co_u32_e32 v109, vcc, 0, v121, vcc
	v_mul_f32_e32 v112, v112, v114
	v_mul_f32_e32 v114, v115, v119
	v_mul_f32_e32 v110, v110, v112
	v_mul_f32_e32 v112, 0xbfb8aa3b, v114
	global_store_short v[108:109], v113, off offset:1536
	v_exp_f32_e32 v113, v112
	v_add_co_u32_e32 v112, vcc, s2, v120
	v_cvt_pk_bf16_f32 v110, v110, s0
	v_add_f32_e32 v113, 1.0, v113
	v_rcp_f32_e32 v115, v113
	v_addc_co_u32_e32 v113, vcc, 0, v121, vcc
	global_store_short v[112:113], v110, off offset:3072
	v_mul_f32_e32 v110, v111, v119
	v_mul_f32_e32 v111, v114, v115
	v_mul_f32_e32 v104, v104, v116
	v_mul_f32_e32 v110, v110, v111
	v_mul_f32_e32 v111, 0xbfb8aa3b, v104
	v_exp_f32_e32 v115, v111
	v_cvt_pk_bf16_f32 v114, v110, s0
	v_add_co_u32_e32 v110, vcc, s3, v120
	v_mul_f32_e32 v105, v105, v117
	s_nop 0
	v_addc_co_u32_e32 v111, vcc, 0, v121, vcc
	global_store_short v[110:111], v114, off offset:512
	v_add_f32_e32 v114, 1.0, v115
	v_rcp_f32_e32 v114, v114
	v_mul_f32_e32 v115, 0xbfb8aa3b, v105
	v_exp_f32_e32 v115, v115
	v_mul_f32_e32 v100, v100, v116
	v_mul_f32_e32 v104, v104, v114
	v_mul_f32_e32 v100, v100, v104
	v_add_f32_e32 v104, 1.0, v115
	v_rcp_f32_e32 v104, v104
	v_cvt_pk_bf16_f32 v100, v100, s0
	global_store_short v[120:121], v100, off offset:128
	v_mul_f32_e32 v100, v101, v117
	v_mul_f32_e32 v101, v105, v104
	v_mul_f32_e32 v104, v106, v118
	v_mul_f32_e32 v105, 0xbfb8aa3b, v104
	v_exp_f32_e32 v105, v105
	v_mul_f32_e32 v100, v100, v101
	v_cvt_pk_bf16_f32 v100, v100, s0
	global_store_short v[108:109], v100, off offset:1664
	v_add_f32_e32 v100, 1.0, v105
	v_mul_f32_e32 v101, v107, v119
	v_rcp_f32_e32 v100, v100
	v_mul_f32_e32 v105, 0xbfb8aa3b, v101
	v_exp_f32_e32 v105, v105
	v_mul_f32_e32 v102, v102, v118
	v_mul_f32_e32 v100, v104, v100
	v_mul_f32_e32 v100, v102, v100
	v_add_f32_e32 v102, 1.0, v105
	v_rcp_f32_e32 v102, v102
	v_cvt_pk_bf16_f32 v100, v100, s0
	v_or_b32_e32 v106, 32, v135
	global_store_short v[112:113], v100, off offset:3200
	v_lshl_add_u32 v100, v106, 2, v144
	v_mul_f32_e32 v104, v103, v119
	v_mul_f32_e32 v105, v101, v102
	ds_read_b128 v[100:103], v100
	v_mul_f32_e32 v104, v104, v105
	v_cvt_pk_bf16_f32 v104, v104, s0
	global_store_short v[110:111], v104, off offset:640
	v_add_u32_e32 v104, s27, v106
	s_waitcnt lgkmcnt(0)
; DI float fexp2(float x) { return __builtin_amdgcn_exp2f(x); }
;     ...
; #pragma unroll
;     for (int ai = 0; ai < 2; ++ai)
; #pragma unroll
;       for (int m = 0; m < 4; ++m) {
;         const int rowb = ai * 128 + wr * 64 + m * 16 + fq * 4;
;         const f32x4 rs4 = *(const f32x4*)(rstdL + rowb);
; #pragma unroll
;         for (int bj = 0; bj < 2; ++bj) {
;           bf16_t* op = e.out + (size_t)(m0 + rowb) * e.ldo + ((n0 + bj * 128 + wc * 32) >> 1) + fr;
; #pragma unroll
;           for (int j = 0; j < 4; ++j) {
;             const float g = acc[ai][bj][m][0][j] * rs4[j], u = acc[ai][bj][m][1][j] * rs4[j];
;             const float rv = g * __builtin_amdgcn_rcpf(1.f + fexp2(-g * LOG2E)) * u;
;             op[(size_t)j * e.ldo] = (bf16_t)(pack2(rv, 0.f) & 0xffffu);
;           }
;         }
;       }
;     __syncthreads();
	v_mul_f32_e32 v96, v96, v100
	v_mul_f32_e32 v105, 0xbfb8aa3b, v96
	v_exp_f32_e32 v106, v105
	v_mul_f32_e32 v97, v97, v101
	v_mul_f32_e32 v107, 0xbfb8aa3b, v97
	v_exp_f32_e32 v107, v107
	v_add_f32_e32 v106, 1.0, v106
	v_rcp_f32_e32 v106, v106
	v_mul_f32_e32 v92, v92, v100
	v_mad_i64_i32 v[104:105], s[0:1], v104, s13, v[0:1]
	v_mul_f32_e32 v96, v96, v106
	v_mul_f32_e32 v92, v92, v96
	v_add_f32_e32 v96, 1.0, v107
	v_rcp_f32_e32 v96, v96
	v_lshl_add_u64 v[104:105], v[104:105], 0, v[132:133]
	v_cvt_pk_bf16_f32 v92, v92, s0
	global_store_short v[104:105], v92, off
	v_mul_f32_e32 v92, v93, v101
	v_mul_f32_e32 v93, v97, v96
	v_mul_f32_e32 v96, v98, v102
	v_mul_f32_e32 v92, v92, v93
	v_mul_f32_e32 v93, 0xbfb8aa3b, v96
	v_exp_f32_e32 v93, v93
	v_cvt_pk_bf16_f32 v97, v92, s0
	v_add_co_u32_e32 v92, vcc, s12, v104
	v_add_f32_e32 v93, 1.0, v93
	v_rcp_f32_e32 v98, v93
	v_mul_f32_e32 v94, v94, v102
	v_addc_co_u32_e32 v93, vcc, 0, v105, vcc
	v_mul_f32_e32 v96, v96, v98
	v_mul_f32_e32 v98, v99, v103
	v_mul_f32_e32 v94, v94, v96
	v_mul_f32_e32 v96, 0xbfb8aa3b, v98
	global_store_short v[92:93], v97, off offset:1536
	v_exp_f32_e32 v97, v96
	v_add_co_u32_e32 v96, vcc, s2, v104
	v_cvt_pk_bf16_f32 v94, v94, s0
	v_add_f32_e32 v97, 1.0, v97
	v_rcp_f32_e32 v99, v97
	v_addc_co_u32_e32 v97, vcc, 0, v105, vcc
	global_store_short v[96:97], v94, off offset:3072
	v_mul_f32_e32 v94, v95, v103
	v_mul_f32_e32 v95, v98, v99
	v_mul_f32_e32 v88, v88, v100
	v_mul_f32_e32 v94, v94, v95
	v_mul_f32_e32 v95, 0xbfb8aa3b, v88
	v_exp_f32_e32 v99, v95
	v_cvt_pk_bf16_f32 v98, v94, s0
	v_add_co_u32_e32 v94, vcc, s3, v104
	v_mul_f32_e32 v89, v89, v101
	s_nop 0
	v_addc_co_u32_e32 v95, vcc, 0, v105, vcc
	global_store_short v[94:95], v98, off offset:512
	v_add_f32_e32 v98, 1.0, v99
	v_rcp_f32_e32 v98, v98
	v_mul_f32_e32 v99, 0xbfb8aa3b, v89
	v_exp_f32_e32 v99, v99
	v_mul_f32_e32 v84, v84, v100
	v_mul_f32_e32 v88, v88, v98
	v_mul_f32_e32 v84, v84, v88
	v_add_f32_e32 v88, 1.0, v99
	v_rcp_f32_e32 v88, v88
	v_cvt_pk_bf16_f32 v84, v84, s0
	global_store_short v[104:105], v84, off offset:128
	v_mul_f32_e32 v84, v85, v101
	v_mul_f32_e32 v85, v89, v88
	v_mul_f32_e32 v88, v90, v102
	v_mul_f32_e32 v89, 0xbfb8aa3b, v88
	v_exp_f32_e32 v89, v89
	v_mul_f32_e32 v84, v84, v85
	v_cvt_pk_bf16_f32 v84, v84, s0
	global_store_short v[92:93], v84, off offset:1664
	v_add_f32_e32 v84, 1.0, v89
	v_mul_f32_e32 v85, v91, v103
	v_rcp_f32_e32 v84, v84
	v_mul_f32_e32 v89, 0xbfb8aa3b, v85
	v_exp_f32_e32 v89, v89
	v_mul_f32_e32 v86, v86, v102
	v_mul_f32_e32 v84, v88, v84
	v_mul_f32_e32 v84, v86, v84
	v_add_f32_e32 v86, 1.0, v89
	v_rcp_f32_e32 v86, v86
	v_cvt_pk_bf16_f32 v84, v84, s0
	v_or_b32_e32 v90, 48, v135
	global_store_short v[96:97], v84, off offset:3200
	v_lshl_add_u32 v84, v90, 2, v144
	v_mul_f32_e32 v88, v87, v103
	v_mul_f32_e32 v89, v85, v86
	ds_read_b128 v[84:87], v84
	v_mul_f32_e32 v88, v88, v89
	v_cvt_pk_bf16_f32 v88, v88, s0
	global_store_short v[94:95], v88, off offset:640
	v_add_u32_e32 v88, s27, v90
	s_waitcnt lgkmcnt(0)
	v_mul_f32_e32 v80, v80, v84
	v_mul_f32_e32 v89, 0xbfb8aa3b, v80
	v_exp_f32_e32 v90, v89
	v_mul_f32_e32 v81, v81, v85
	v_mul_f32_e32 v91, 0xbfb8aa3b, v81
	v_exp_f32_e32 v91, v91
	v_add_f32_e32 v90, 1.0, v90
	v_rcp_f32_e32 v90, v90
	v_mul_f32_e32 v76, v76, v84
	v_mad_i64_i32 v[88:89], s[0:1], v88, s13, v[0:1]
	v_mul_f32_e32 v80, v80, v90
	v_mul_f32_e32 v76, v76, v80
	v_add_f32_e32 v80, 1.0, v91
	v_rcp_f32_e32 v80, v80
	v_lshl_add_u64 v[88:89], v[88:89], 0, v[132:133]
	v_cvt_pk_bf16_f32 v76, v76, s0
	global_store_short v[88:89], v76, off
	v_mul_f32_e32 v76, v77, v85
	v_mul_f32_e32 v77, v81, v80
	v_mul_f32_e32 v76, v76, v77
	v_mul_f32_e32 v77, v82, v86
	v_mul_f32_e32 v80, 0xbfb8aa3b, v77
	v_exp_f32_e32 v81, v80
	v_add_co_u32_e32 v80, vcc, s12, v88
	v_cvt_pk_bf16_f32 v76, v76, s0
	v_add_f32_e32 v81, 1.0, v81
	v_rcp_f32_e32 v82, v81
	v_addc_co_u32_e32 v81, vcc, 0, v89, vcc
	global_store_short v[80:81], v76, off offset:1536
	v_mul_f32_e32 v76, v78, v86
	v_mul_f32_e32 v77, v77, v82
	v_mul_f32_e32 v76, v76, v77
	v_mul_f32_e32 v77, v83, v87
	v_mul_f32_e32 v78, 0xbfb8aa3b, v77
	v_exp_f32_e32 v78, v78
	v_add_co_u32_e32 v82, vcc, s2, v88
	v_cvt_pk_bf16_f32 v76, v76, s0
	v_add_f32_e32 v78, 1.0, v78
	v_rcp_f32_e32 v78, v78
	v_addc_co_u32_e32 v83, vcc, 0, v89, vcc
	global_store_short v[82:83], v76, off offset:3072
	v_mul_f32_e32 v76, v79, v87
	v_mul_f32_e32 v77, v77, v78
	v_mul_f32_e32 v72, v72, v84
	v_mul_f32_e32 v76, v76, v77
	v_mul_f32_e32 v77, 0xbfb8aa3b, v72
	v_exp_f32_e32 v79, v77
	v_cvt_pk_bf16_f32 v78, v76, s0
	v_add_co_u32_e32 v76, vcc, s3, v88
	v_mul_f32_e32 v73, v73, v85
	s_nop 0
	v_addc_co_u32_e32 v77, vcc, 0, v89, vcc
	global_store_short v[76:77], v78, off offset:512
	v_add_f32_e32 v78, 1.0, v79
	v_rcp_f32_e32 v78, v78
	v_mul_f32_e32 v79, 0xbfb8aa3b, v73
	v_exp_f32_e32 v79, v79
	v_mul_f32_e32 v68, v68, v84
	v_mul_f32_e32 v72, v72, v78
	v_mul_f32_e32 v68, v68, v72
	v_add_f32_e32 v72, 1.0, v79
	v_rcp_f32_e32 v72, v72
	v_cvt_pk_bf16_f32 v68, v68, s0
	global_store_short v[88:89], v68, off offset:128
	v_mul_f32_e32 v68, v69, v85
	v_mul_f32_e32 v69, v73, v72
	v_mul_f32_e32 v72, v74, v86
	v_mul_f32_e32 v73, 0xbfb8aa3b, v72
	v_exp_f32_e32 v73, v73
	v_mul_f32_e32 v68, v68, v69
	v_cvt_pk_bf16_f32 v68, v68, s0
	global_store_short v[80:81], v68, off offset:1664
	v_add_f32_e32 v68, 1.0, v73
	v_mul_f32_e32 v69, v75, v87
	v_rcp_f32_e32 v68, v68
	v_mul_f32_e32 v73, 0xbfb8aa3b, v69
	v_exp_f32_e32 v73, v73
	v_mul_f32_e32 v70, v70, v86
	v_mul_f32_e32 v68, v72, v68
	v_mul_f32_e32 v68, v70, v68
	v_add_f32_e32 v70, 1.0, v73
	v_rcp_f32_e32 v70, v70
	v_cvt_pk_bf16_f32 v68, v68, s0
	global_store_short v[82:83], v68, off offset:3200
	v_mul_f32_e32 v68, v71, v87
	v_mul_f32_e32 v69, v69, v70
	ds_read_b128 v[70:73], v134 offset:512
	v_mul_f32_e32 v68, v68, v69
	v_cvt_pk_bf16_f32 v68, v68, s0
	global_store_short v[76:77], v68, off offset:640
	v_add_u32_e32 v68, 0x80, v3
	s_waitcnt lgkmcnt(0)
; DI float fexp2(float x) { return __builtin_amdgcn_exp2f(x); }
;     ...
; #pragma unroll
;     for (int ai = 0; ai < 2; ++ai)
; #pragma unroll
;       for (int m = 0; m < 4; ++m) {
;         const int rowb = ai * 128 + wr * 64 + m * 16 + fq * 4;
;         const f32x4 rs4 = *(const f32x4*)(rstdL + rowb);
; #pragma unroll
;         for (int bj = 0; bj < 2; ++bj) {
;           bf16_t* op = e.out + (size_t)(m0 + rowb) * e.ldo + ((n0 + bj * 128 + wc * 32) >> 1) + fr;
; #pragma unroll
;           for (int j = 0; j < 4; ++j) {
;             const float g = acc[ai][bj][m][0][j] * rs4[j], u = acc[ai][bj][m][1][j] * rs4[j];
;             const float rv = g * __builtin_amdgcn_rcpf(1.f + fexp2(-g * LOG2E)) * u;
;             op[(size_t)j * e.ldo] = (bf16_t)(pack2(rv, 0.f) & 0xffffu);
;           }
;         }
;       }
;     __syncthreads();
	v_mul_f32_e32 v64, v64, v70
	v_mul_f32_e32 v69, 0xbfb8aa3b, v64
	v_exp_f32_e32 v74, v69
	v_mul_f32_e32 v65, v65, v71
	v_mul_f32_e32 v75, 0xbfb8aa3b, v65
	v_exp_f32_e32 v75, v75
	v_add_f32_e32 v74, 1.0, v74
	v_rcp_f32_e32 v74, v74
	v_mul_f32_e32 v60, v60, v70
	v_mad_i64_i32 v[68:69], s[0:1], v68, s13, v[0:1]
	v_mul_f32_e32 v64, v64, v74
	v_mul_f32_e32 v60, v60, v64
	v_add_f32_e32 v64, 1.0, v75
	v_rcp_f32_e32 v64, v64
	v_lshl_add_u64 v[68:69], v[68:69], 0, v[132:133]
	v_cvt_pk_bf16_f32 v60, v60, s0
	global_store_short v[68:69], v60, off
	v_mul_f32_e32 v60, v61, v71
	v_mul_f32_e32 v61, v65, v64
	v_mul_f32_e32 v64, v66, v72
	v_mul_f32_e32 v60, v60, v61
	v_mul_f32_e32 v61, 0xbfb8aa3b, v64
	v_exp_f32_e32 v61, v61
	v_cvt_pk_bf16_f32 v65, v60, s0
	v_add_co_u32_e32 v60, vcc, s12, v68
	v_add_f32_e32 v61, 1.0, v61
	v_rcp_f32_e32 v66, v61
	v_mul_f32_e32 v62, v62, v72
	v_addc_co_u32_e32 v61, vcc, 0, v69, vcc
	v_mul_f32_e32 v64, v64, v66
	v_mul_f32_e32 v66, v67, v73
	v_mul_f32_e32 v62, v62, v64
	v_mul_f32_e32 v64, 0xbfb8aa3b, v66
	global_store_short v[60:61], v65, off offset:1536
	v_exp_f32_e32 v65, v64
	v_add_co_u32_e32 v64, vcc, s2, v68
	v_cvt_pk_bf16_f32 v62, v62, s0
	v_add_f32_e32 v65, 1.0, v65
	v_rcp_f32_e32 v67, v65
	v_addc_co_u32_e32 v65, vcc, 0, v69, vcc
	global_store_short v[64:65], v62, off offset:3072
	v_mul_f32_e32 v62, v63, v73
	v_mul_f32_e32 v63, v66, v67
	v_mul_f32_e32 v56, v56, v70
	v_mul_f32_e32 v62, v62, v63
	v_mul_f32_e32 v63, 0xbfb8aa3b, v56
	v_exp_f32_e32 v67, v63
	v_cvt_pk_bf16_f32 v66, v62, s0
	v_add_co_u32_e32 v62, vcc, s3, v68
	v_mul_f32_e32 v57, v57, v71
	s_nop 0
	v_addc_co_u32_e32 v63, vcc, 0, v69, vcc
	global_store_short v[62:63], v66, off offset:512
	v_add_f32_e32 v66, 1.0, v67
	v_rcp_f32_e32 v66, v66
	v_mul_f32_e32 v67, 0xbfb8aa3b, v57
	v_exp_f32_e32 v67, v67
	v_mul_f32_e32 v52, v52, v70
	v_mul_f32_e32 v56, v56, v66
	v_mul_f32_e32 v52, v52, v56
	v_add_f32_e32 v56, 1.0, v67
	v_rcp_f32_e32 v56, v56
	v_cvt_pk_bf16_f32 v52, v52, s0
	global_store_short v[68:69], v52, off offset:128
	v_mul_f32_e32 v52, v53, v71
	v_mul_f32_e32 v53, v57, v56
	v_mul_f32_e32 v56, v58, v72
	v_mul_f32_e32 v57, 0xbfb8aa3b, v56
	v_exp_f32_e32 v57, v57
	v_mul_f32_e32 v52, v52, v53
	v_cvt_pk_bf16_f32 v52, v52, s0
	global_store_short v[60:61], v52, off offset:1664
	v_add_f32_e32 v52, 1.0, v57
	v_mul_f32_e32 v53, v59, v73
	v_rcp_f32_e32 v52, v52
	v_mul_f32_e32 v57, 0xbfb8aa3b, v53
	v_exp_f32_e32 v57, v57
	v_mul_f32_e32 v54, v54, v72
	v_mul_f32_e32 v52, v56, v52
	v_mul_f32_e32 v52, v54, v52
	v_add_f32_e32 v54, 1.0, v57
	v_rcp_f32_e32 v54, v54
	v_cvt_pk_bf16_f32 v52, v52, s0
	global_store_short v[64:65], v52, off offset:3200
	v_mul_f32_e32 v56, v55, v73
	v_mul_f32_e32 v57, v53, v54
	ds_read_b128 v[52:55], v134 offset:576
	v_mul_f32_e32 v56, v56, v57
	v_cvt_pk_bf16_f32 v56, v56, s0
	global_store_short v[62:63], v56, off offset:640
	v_add_u32_e32 v56, 0x90, v3
	s_waitcnt lgkmcnt(0)
	v_mul_f32_e32 v48, v48, v52
	v_mul_f32_e32 v57, 0xbfb8aa3b, v48
	v_exp_f32_e32 v58, v57
	v_mul_f32_e32 v49, v49, v53
	v_mul_f32_e32 v59, 0xbfb8aa3b, v49
	v_exp_f32_e32 v59, v59
	v_add_f32_e32 v58, 1.0, v58
	v_rcp_f32_e32 v58, v58
	v_mul_f32_e32 v44, v44, v52
	v_mad_i64_i32 v[56:57], s[0:1], v56, s13, v[0:1]
	v_mul_f32_e32 v48, v48, v58
	v_mul_f32_e32 v44, v44, v48
	v_add_f32_e32 v48, 1.0, v59
	v_rcp_f32_e32 v48, v48
	v_lshl_add_u64 v[56:57], v[56:57], 0, v[132:133]
	v_cvt_pk_bf16_f32 v44, v44, s0
	global_store_short v[56:57], v44, off
	v_mul_f32_e32 v44, v45, v53
	v_mul_f32_e32 v45, v49, v48
	v_mul_f32_e32 v48, v50, v54
	v_mul_f32_e32 v44, v44, v45
	v_mul_f32_e32 v45, 0xbfb8aa3b, v48
	v_exp_f32_e32 v45, v45
	v_cvt_pk_bf16_f32 v49, v44, s0
	v_add_co_u32_e32 v44, vcc, s12, v56
	v_add_f32_e32 v45, 1.0, v45
	v_rcp_f32_e32 v50, v45
	v_mul_f32_e32 v46, v46, v54
	v_addc_co_u32_e32 v45, vcc, 0, v57, vcc
	v_mul_f32_e32 v48, v48, v50
	v_mul_f32_e32 v50, v51, v55
	v_mul_f32_e32 v46, v46, v48
	v_mul_f32_e32 v48, 0xbfb8aa3b, v50
	global_store_short v[44:45], v49, off offset:1536
	v_exp_f32_e32 v49, v48
	v_add_co_u32_e32 v48, vcc, s2, v56
	v_cvt_pk_bf16_f32 v46, v46, s0
	v_add_f32_e32 v49, 1.0, v49
	v_rcp_f32_e32 v51, v49
	v_addc_co_u32_e32 v49, vcc, 0, v57, vcc
	global_store_short v[48:49], v46, off offset:3072
	v_mul_f32_e32 v46, v47, v55
	v_mul_f32_e32 v47, v50, v51
	v_mul_f32_e32 v40, v40, v52
	v_mul_f32_e32 v46, v46, v47
	v_mul_f32_e32 v47, 0xbfb8aa3b, v40
	v_exp_f32_e32 v51, v47
	v_cvt_pk_bf16_f32 v50, v46, s0
	v_add_co_u32_e32 v46, vcc, s3, v56
	v_mul_f32_e32 v41, v41, v53
	s_nop 0
	v_addc_co_u32_e32 v47, vcc, 0, v57, vcc
	global_store_short v[46:47], v50, off offset:512
	v_add_f32_e32 v50, 1.0, v51
	v_rcp_f32_e32 v50, v50
	v_mul_f32_e32 v51, 0xbfb8aa3b, v41
	v_exp_f32_e32 v51, v51
	v_mul_f32_e32 v36, v36, v52
	v_mul_f32_e32 v40, v40, v50
	v_mul_f32_e32 v36, v36, v40
	v_add_f32_e32 v40, 1.0, v51
	v_rcp_f32_e32 v40, v40
	v_cvt_pk_bf16_f32 v36, v36, s0
	global_store_short v[56:57], v36, off offset:128
	v_mul_f32_e32 v36, v37, v53
	v_mul_f32_e32 v37, v41, v40
	v_mul_f32_e32 v40, v42, v54
	v_mul_f32_e32 v41, 0xbfb8aa3b, v40
	v_exp_f32_e32 v41, v41
	v_mul_f32_e32 v36, v36, v37
	v_cvt_pk_bf16_f32 v36, v36, s0
	global_store_short v[44:45], v36, off offset:1664
	v_add_f32_e32 v36, 1.0, v41
	v_mul_f32_e32 v37, v43, v55
	v_rcp_f32_e32 v36, v36
	v_mul_f32_e32 v41, 0xbfb8aa3b, v37
	v_exp_f32_e32 v41, v41
	v_mul_f32_e32 v38, v38, v54
	v_mul_f32_e32 v36, v40, v36
	v_mul_f32_e32 v36, v38, v36
	v_add_f32_e32 v38, 1.0, v41
	v_rcp_f32_e32 v38, v38
	v_cvt_pk_bf16_f32 v36, v36, s0
	global_store_short v[48:49], v36, off offset:3200
	v_mul_f32_e32 v40, v39, v55
	v_mul_f32_e32 v41, v37, v38
	ds_read_b128 v[36:39], v134 offset:640
	v_mul_f32_e32 v40, v40, v41
	v_cvt_pk_bf16_f32 v40, v40, s0
	global_store_short v[46:47], v40, off offset:640
	v_add_u32_e32 v40, 0xa0, v3
	s_waitcnt lgkmcnt(0)
; DI float fexp2(float x) { return __builtin_amdgcn_exp2f(x); }
;     ...
; #pragma unroll
;     for (int ai = 0; ai < 2; ++ai)
; #pragma unroll
;       for (int m = 0; m < 4; ++m) {
;         const int rowb = ai * 128 + wr * 64 + m * 16 + fq * 4;
;         const f32x4 rs4 = *(const f32x4*)(rstdL + rowb);
; #pragma unroll
;         for (int bj = 0; bj < 2; ++bj) {
;           bf16_t* op = e.out + (size_t)(m0 + rowb) * e.ldo + ((n0 + bj * 128 + wc * 32) >> 1) + fr;
; #pragma unroll
;           for (int j = 0; j < 4; ++j) {
;             const float g = acc[ai][bj][m][0][j] * rs4[j], u = acc[ai][bj][m][1][j] * rs4[j];
;             const float rv = g * __builtin_amdgcn_rcpf(1.f + fexp2(-g * LOG2E)) * u;
;             op[(size_t)j * e.ldo] = (bf16_t)(pack2(rv, 0.f) & 0xffffu);
;           }
;         }
;       }
;     __syncthreads();
	v_mul_f32_e32 v32, v32, v36
	v_mul_f32_e32 v41, 0xbfb8aa3b, v32
	v_exp_f32_e32 v42, v41
	v_mul_f32_e32 v33, v33, v37
	v_mul_f32_e32 v43, 0xbfb8aa3b, v33
	v_exp_f32_e32 v43, v43
	v_add_f32_e32 v42, 1.0, v42
	v_rcp_f32_e32 v42, v42
	v_mul_f32_e32 v28, v28, v36
	v_mad_i64_i32 v[40:41], s[0:1], v40, s13, v[0:1]
	v_mul_f32_e32 v32, v32, v42
	v_mul_f32_e32 v28, v28, v32
	v_add_f32_e32 v32, 1.0, v43
	v_rcp_f32_e32 v32, v32
	v_lshl_add_u64 v[40:41], v[40:41], 0, v[132:133]
	v_cvt_pk_bf16_f32 v28, v28, s0
	global_store_short v[40:41], v28, off
	v_mul_f32_e32 v28, v29, v37
	v_mul_f32_e32 v29, v33, v32
	v_mul_f32_e32 v28, v28, v29
	v_mul_f32_e32 v29, v34, v38
	v_mul_f32_e32 v32, 0xbfb8aa3b, v29
	v_exp_f32_e32 v33, v32
	v_add_co_u32_e32 v32, vcc, s12, v40
	v_cvt_pk_bf16_f32 v28, v28, s0
	v_add_f32_e32 v33, 1.0, v33
	v_rcp_f32_e32 v34, v33
	v_addc_co_u32_e32 v33, vcc, 0, v41, vcc
	global_store_short v[32:33], v28, off offset:1536
	v_mul_f32_e32 v28, v30, v38
	v_mul_f32_e32 v29, v29, v34
	v_mul_f32_e32 v28, v28, v29
	v_mul_f32_e32 v29, v35, v39
	v_mul_f32_e32 v30, 0xbfb8aa3b, v29
	v_exp_f32_e32 v30, v30
	v_add_co_u32_e32 v34, vcc, s2, v40
	v_cvt_pk_bf16_f32 v28, v28, s0
	v_add_f32_e32 v30, 1.0, v30
	v_rcp_f32_e32 v30, v30
	v_addc_co_u32_e32 v35, vcc, 0, v41, vcc
	global_store_short v[34:35], v28, off offset:3072
	v_mul_f32_e32 v28, v31, v39
	v_mul_f32_e32 v29, v29, v30
	v_mul_f32_e32 v24, v24, v36
	v_mul_f32_e32 v28, v28, v29
	v_mul_f32_e32 v29, 0xbfb8aa3b, v24
	v_exp_f32_e32 v31, v29
	v_cvt_pk_bf16_f32 v30, v28, s0
	v_add_co_u32_e32 v28, vcc, s3, v40
	v_mul_f32_e32 v25, v25, v37
	s_nop 0
	v_addc_co_u32_e32 v29, vcc, 0, v41, vcc
	global_store_short v[28:29], v30, off offset:512
	v_add_f32_e32 v30, 1.0, v31
	v_rcp_f32_e32 v30, v30
	v_mul_f32_e32 v31, 0xbfb8aa3b, v25
	v_exp_f32_e32 v31, v31
	v_mul_f32_e32 v20, v20, v36
	v_mul_f32_e32 v24, v24, v30
	v_mul_f32_e32 v20, v20, v24
	v_add_f32_e32 v24, 1.0, v31
	v_rcp_f32_e32 v24, v24
	v_cvt_pk_bf16_f32 v20, v20, s0
	global_store_short v[40:41], v20, off offset:128
	v_mul_f32_e32 v20, v21, v37
	v_mul_f32_e32 v21, v25, v24
	v_mul_f32_e32 v24, v26, v38
	v_mul_f32_e32 v25, 0xbfb8aa3b, v24
	v_exp_f32_e32 v25, v25
	v_mul_f32_e32 v20, v20, v21
	v_cvt_pk_bf16_f32 v20, v20, s0
	global_store_short v[32:33], v20, off offset:1664
	v_add_f32_e32 v20, 1.0, v25
	v_mul_f32_e32 v21, v27, v39
	v_rcp_f32_e32 v20, v20
	v_mul_f32_e32 v25, 0xbfb8aa3b, v21
	v_exp_f32_e32 v25, v25
	v_mul_f32_e32 v22, v22, v38
	v_mul_f32_e32 v20, v24, v20
	v_mul_f32_e32 v20, v22, v20
	v_add_f32_e32 v22, 1.0, v25
	v_rcp_f32_e32 v22, v22
	v_cvt_pk_bf16_f32 v20, v20, s0
	global_store_short v[34:35], v20, off offset:3200
	v_mul_f32_e32 v24, v23, v39
	v_mul_f32_e32 v25, v21, v22
	ds_read_b128 v[20:23], v134 offset:704
	v_mul_f32_e32 v24, v24, v25
	v_cvt_pk_bf16_f32 v24, v24, s0
	global_store_short v[28:29], v24, off offset:640
	v_add_u32_e32 v3, 0xb0, v3
	s_waitcnt lgkmcnt(0)
	v_mul_f32_e32 v16, v16, v20
	v_mul_f32_e32 v24, 0xbfb8aa3b, v16
	v_exp_f32_e32 v24, v24
	v_mad_i64_i32 v[0:1], s[0:1], v3, s13, v[0:1]
	v_mul_f32_e32 v17, v17, v21
	v_add_f32_e32 v3, 1.0, v24
	v_rcp_f32_e32 v3, v3
	v_mul_f32_e32 v24, 0xbfb8aa3b, v17
	v_exp_f32_e32 v24, v24
	v_mul_f32_e32 v12, v12, v20
	v_mul_f32_e32 v3, v16, v3
	v_mul_f32_e32 v3, v12, v3
	v_add_f32_e32 v12, 1.0, v24
	v_rcp_f32_e32 v12, v12
	v_lshl_add_u64 v[0:1], v[0:1], 0, v[132:133]
	v_cvt_pk_bf16_f32 v3, v3, s0
	global_store_short v[0:1], v3, off
	v_mul_f32_e32 v3, v13, v21
	v_mul_f32_e32 v12, v17, v12
	v_mul_f32_e32 v16, v18, v22
	v_mul_f32_e32 v3, v3, v12
	v_mul_f32_e32 v12, 0xbfb8aa3b, v16
	v_exp_f32_e32 v13, v12
	v_add_co_u32_e32 v12, vcc, s12, v0
	v_cvt_pk_bf16_f32 v3, v3, s0
	v_add_f32_e32 v13, 1.0, v13
	v_rcp_f32_e32 v17, v13
	v_addc_co_u32_e32 v13, vcc, 0, v1, vcc
	global_store_short v[12:13], v3, off offset:1536
	v_mul_f32_e32 v3, v14, v22
	v_mul_f32_e32 v14, v16, v17
	v_mul_f32_e32 v3, v3, v14
	v_mul_f32_e32 v14, v19, v23
	v_mul_f32_e32 v16, 0xbfb8aa3b, v14
	v_exp_f32_e32 v17, v16
	v_add_co_u32_e32 v16, vcc, s2, v0
	v_cvt_pk_bf16_f32 v3, v3, s0
	v_add_f32_e32 v17, 1.0, v17
	v_rcp_f32_e32 v18, v17
	v_addc_co_u32_e32 v17, vcc, 0, v1, vcc
	v_mul_f32_e32 v8, v8, v20
	global_store_short v[16:17], v3, off offset:3072
	v_mul_f32_e32 v3, v15, v23
	v_mul_f32_e32 v15, 0xbfb8aa3b, v8
	v_mul_f32_e32 v14, v14, v18
	v_exp_f32_e32 v18, v15
	v_mul_f32_e32 v3, v3, v14
	v_add_co_u32_e32 v14, vcc, s3, v0
	v_cvt_pk_bf16_f32 v3, v3, s0
	s_nop 0
	v_addc_co_u32_e32 v15, vcc, 0, v1, vcc
	global_store_short v[14:15], v3, off offset:512
	v_add_f32_e32 v3, 1.0, v18
	v_mul_f32_e32 v9, v9, v21
	v_rcp_f32_e32 v3, v3
	v_mul_f32_e32 v18, 0xbfb8aa3b, v9
	v_exp_f32_e32 v18, v18
	v_mul_f32_e32 v4, v4, v20
	v_mul_f32_e32 v3, v8, v3
	v_mul_f32_e32 v3, v4, v3
	v_add_f32_e32 v4, 1.0, v18
	v_rcp_f32_e32 v4, v4
	v_cvt_pk_bf16_f32 v3, v3, s0
	global_store_short v[0:1], v3, off offset:128
	v_mul_f32_e32 v3, v10, v22
	v_mul_f32_e32 v1, v9, v4
	v_mul_f32_e32 v4, 0xbfb8aa3b, v3
	v_exp_f32_e32 v4, v4
	v_mul_f32_e32 v0, v5, v21
	v_mul_f32_e32 v0, v0, v1
	v_cvt_pk_bf16_f32 v0, v0, s0
	v_mul_f32_e32 v1, v11, v23
	global_store_short v[12:13], v0, off offset:1664
	v_add_f32_e32 v0, 1.0, v4
	v_mul_f32_e32 v4, 0xbfb8aa3b, v1
	v_rcp_f32_e32 v0, v0
	v_exp_f32_e32 v4, v4
	v_mul_f32_e32 v5, v6, v22
	v_mov_b32_e32 v234, 0x21010
	v_mul_f32_e32 v0, v3, v0
	v_add_f32_e32 v3, 1.0, v4
	v_rcp_f32_e32 v3, v3
	v_mul_f32_e32 v0, v5, v0
	v_cvt_pk_bf16_f32 v0, v0, s0
	global_store_short v[16:17], v0, off offset:3200
	v_mul_f32_e32 v0, v7, v23
	v_mul_f32_e32 v1, v1, v3
	v_mul_f32_e32 v0, v0, v1
	v_cvt_pk_bf16_f32 v0, v0, s0
	global_store_short v[14:15], v0, off offset:640
	s_waitcnt vmcnt(63) expcnt(7) lgkmcnt(15)
	s_barrier

; DI int tid_opaque() { int t = threadIdx.x; asm volatile("" : "+v"(t)); return t; }
;     ...
;   if (EPI == EPI_GU && nm0 >= 0) {
;     const int t = tid_opaque();
;     STAGE8(SB8(0, 0), Bt, K, nn0, 0); STAGE8(SA8(0, 0), A, lda, nm0, 0);
;     STAGE8(SB8(0, 1), Bt, K, nn0 + 128, 0); STAGE8(SA8(0, 1), A, lda, nm0 + 128, 0);
;   }
;     ...
;   if (t < 256) {
;     float rs = 1.f;
;     if (e.ss) {
;       const float* sp = e.ss + (size_t)(m0 + t) * e.nss;
;       float s = 0.f;
;       for (int i = 0; i < e.nss; ++i) s += sp[i];
.LBB0_1262:
	s_or_b64 exec, exec, s[8:9]
	v_readlane_b32 s8, v252, 1
	s_add_i32 s25, s25, s8
	v_readlane_b32 s9, v252, 2
	s_cmpk_lt_i32 s25, 0x500
	s_cselect_b64 s[8:9], -1, 0
	s_cmpk_gt_i32 s25, 0x4ff
	s_waitcnt vmcnt(0)
	s_barrier
	v_add_u32_e32 v222, s27, v3
	v_ashrrev_i32_e32 v223, 31, v222
	v_lshlrev_b64 v[222:223], 6, v[222:223]
	v_lshl_add_u64 v[222:223], s[38:39], 0, v[222:223]
	global_load_dwordx4 v[236:239], v[222:223], off
	global_load_dwordx4 v[240:243], v[222:223], off offset:16
	global_load_dwordx4 v[244:247], v[222:223], off offset:32
	global_load_dwordx4 v[248:251], v[222:223], off offset:48
	s_cbranch_scc1 .Lp7_nochain
	v_mov_b32_e32 v0, v224
	s_lshl_b32 s12, s25, 2
	v_ashrrev_i32_e32 v1, 31, v0
	v_lshrrev_b32_e32 v1, 26, v1
	v_lshlrev_b32_e32 v140, 4, v0
	v_add_u32_e32 v1, v0, v1
	v_bfe_i32 v0, v0, 27, 1
	v_lshrrev_b32_e32 v0, 22, v0
	v_add_u32_e32 v0, v140, v0
	v_and_b32_e32 v0, 0xfffffc00, v0
	v_sub_u32_e32 v0, v140, v0
	v_lshrrev_b32_e32 v132, 4, v0
	v_bitop3_b32 v132, v132, v0, 32 bitop3:0x6c
	v_ashrrev_i32_e32 v0, 31, v0
	v_ashrrev_i32_e32 v1, 6, v1
	v_lshrrev_b32_e32 v0, 26, v0
	v_lshlrev_b32_e32 v133, 3, v1
	v_add_u32_e32 v0, v132, v0
	v_and_b32_e32 v133, -16, v133
	v_ashrrev_i32_e32 v134, 6, v0
	s_and_b32 s12, s12, 0xffffff00
	v_add_u32_e32 v0, v134, v133
	v_mul_i32_i24_e32 v133, 64, v134
	s_lshl_b32 s1, s25, 19
	s_ashr_i32 s13, s12, 31
	v_lshlrev_b32_e32 v1, 5, v1
	v_sub_u32_e32 v132, v132, v133
	v_mov_b32_e32 v139, 1
	s_and_b32 s1, s1, 0x1f80000
	s_lshl_b64 s[14:15], s[12:13], 11
	v_and_b32_e32 v1, 32, v1
	v_ashrrev_i16_sdwa v132, v139, sext(v132) dst_sel:DWORD dst_unused:UNUSED_PAD src0_sel:DWORD src1_sel:BYTE_0
	s_add_u32 s14, s4, s14
	v_add_u32_sdwa v132, v1, sext(v132) dst_sel:DWORD dst_unused:UNUSED_PAD src0_sel:DWORD src1_sel:WORD_0
	v_ashrrev_i32_e32 v1, 31, v0
	s_addc_u32 s15, s5, s15
	v_lshlrev_b64 v[0:1], 11, v[0:1]
	v_ashrrev_i32_e32 v133, 31, v132
	v_add_u32_e32 v136, 0x10000, v140
	v_lshl_add_u64 v[134:135], s[14:15], 0, v[0:1]
	v_lshlrev_b64 v[132:133], 1, v[132:133]
	v_readfirstlane_b32 s13, v136
	v_lshl_add_u64 v[134:135], v[134:135], 0, v[132:133]
	s_mov_b32 m0, s13
	v_add_u32_e32 v141, 0x2000, v140
	global_load_lds_dwordx4 v[134:135], off
	v_ashrrev_i32_e32 v134, 31, v141
	v_lshrrev_b32_e32 v134, 22, v134
	v_add_u32_e32 v134, v141, v134
	v_ashrrev_i32_e32 v135, 10, v134
	v_mul_i32_i24_e32 v134, 0x400, v135
	v_sub_u32_e32 v134, v141, v134
	v_lshrrev_b32_e32 v136, 4, v134
	v_bitop3_b32 v136, v136, v134, 32 bitop3:0x6c
	v_ashrrev_i32_e32 v137, 31, v136
	v_lshrrev_b32_e32 v137, 26, v137
	v_add_u32_e32 v137, v136, v137
	v_lshlrev_b32_e32 v134, 3, v135
	v_ashrrev_i32_e32 v138, 6, v137
	v_and_b32_e32 v137, 0xc0, v137
	v_and_b32_e32 v134, -16, v134
	v_lshlrev_b32_e32 v135, 5, v135
	v_sub_u32_e32 v136, v136, v137
	v_add_u32_e32 v134, v138, v134
	v_and_b32_e32 v135, 32, v135
	v_ashrrev_i16_sdwa v136, v139, sext(v136) dst_sel:DWORD dst_unused:UNUSED_PAD src0_sel:DWORD src1_sel:BYTE_0
	v_add_u32_sdwa v136, v135, sext(v136) dst_sel:DWORD dst_unused:UNUSED_PAD src0_sel:DWORD src1_sel:WORD_0
	v_ashrrev_i32_e32 v135, 31, v134
	v_lshlrev_b64 v[134:135], 11, v[134:135]
	v_ashrrev_i32_e32 v137, 31, v136
	v_add_u32_e32 v142, 0x12000, v140
	s_add_u32 s2, s2, s1
	v_lshl_add_u64 v[138:139], s[14:15], 0, v[134:135]
	v_lshlrev_b64 v[136:137], 1, v[136:137]
	v_readfirstlane_b32 s13, v142
	s_addc_u32 s3, s3, 0
	s_bitset1_b32 s12, 7
	v_lshl_add_u64 v[138:139], v[138:139], 0, v[136:137]
	s_mov_b32 m0, s13
	s_ashr_i32 s13, s12, 31
	global_load_lds_dwordx4 v[138:139], off
	v_lshl_add_u64 v[138:139], s[2:3], 0, v[0:1]
	v_readfirstlane_b32 s1, v140
	s_lshl_b64 s[12:13], s[12:13], 11
	v_lshl_add_u64 v[138:139], v[138:139], 0, v[132:133]
	s_mov_b32 m0, s1
	s_add_u32 s12, s4, s12
	global_load_lds_dwordx4 v[138:139], off
	v_lshl_add_u64 v[138:139], s[2:3], 0, v[134:135]
	v_readfirstlane_b32 s1, v141
	s_addc_u32 s13, s5, s13
	v_lshl_add_u64 v[138:139], v[138:139], 0, v[136:137]
	s_mov_b32 m0, s1
	v_add_u32_e32 v141, 0x14000, v140
	s_add_u32 s2, s2, 0x40000
	global_load_lds_dwordx4 v[138:139], off
	v_lshl_add_u64 v[138:139], s[12:13], 0, v[0:1]
	v_readfirstlane_b32 s1, v141
	s_addc_u32 s3, s3, 0
	v_lshl_add_u64 v[138:139], v[138:139], 0, v[132:133]
	s_mov_b32 m0, s1
	v_add_u32_e32 v141, 0x16000, v140
	v_lshl_add_u64 v[0:1], s[2:3], 0, v[0:1]
	global_load_lds_dwordx4 v[138:139], off
	v_lshl_add_u64 v[138:139], s[12:13], 0, v[134:135]
	v_readfirstlane_b32 s1, v141
	v_lshl_add_u64 v[0:1], v[0:1], 0, v[132:133]
	v_add_u32_e32 v132, 0x4000, v140
	v_lshl_add_u64 v[138:139], v[138:139], 0, v[136:137]
	s_mov_b32 m0, s1
	v_readfirstlane_b32 s1, v132
	global_load_lds_dwordx4 v[138:139], off
	s_mov_b32 m0, s1
	v_add_u32_e32 v132, 0x6000, v140
	global_load_lds_dwordx4 v[0:1], off
	v_lshl_add_u64 v[0:1], s[2:3], 0, v[134:135]
	v_readfirstlane_b32 s1, v132
	v_lshl_add_u64 v[0:1], v[0:1], 0, v[136:137]
	s_mov_b32 m0, s1
	s_nop 0
	global_load_lds_dwordx4 v[0:1], off
	s_branch .LBB0_1264

;     ...
;   if (t < 256) {
;     float rs = 1.f;
;     if (e.ss) {
;       const float* sp = e.ss + (size_t)(m0 + t) * e.nss;
;       float s = 0.f;
;       for (int i = 0; i < e.nss; ++i) s += sp[i];
;       rs = rsqrtf(s * e.inv_n + EPS);
;     }
;     ((float*)(smem + SMEM_RSTD))[t] = rs;
;   }
.LBB0_1264:
	s_movk_i32 s1, 0x100
	v_cmp_gt_i32_e32 vcc, s1, v3
	s_and_saveexec_b64 s[2:3], vcc
	s_cbranch_execz .LBB0_1243
	v_mov_b32_e32 v1, 0x358637bd
	s_mov_b32 s1, 0x800000
	s_waitcnt vmcnt(8)
	v_add_f32_e32 v0, 0, v236
	v_add_f32_e32 v0, v0, v237
	v_add_f32_e32 v0, v0, v238
	v_add_f32_e32 v0, v0, v239
	v_add_f32_e32 v0, v0, v240
	v_add_f32_e32 v0, v0, v241
	v_add_f32_e32 v0, v0, v242
	v_add_f32_e32 v0, v0, v243
	v_add_f32_e32 v0, v0, v244
	v_add_f32_e32 v0, v0, v245
	v_add_f32_e32 v0, v0, v246
	v_add_f32_e32 v0, v0, v247
	v_add_f32_e32 v0, v0, v248
	v_add_f32_e32 v0, v0, v249
	v_add_f32_e32 v0, v0, v250
	v_add_f32_e32 v0, v0, v251
	v_fmamk_f32 v0, v0, 0x3a800000, v1
	v_mul_f32_e32 v1, 0x4b800000, v0
	v_cmp_gt_f32_e32 vcc, s1, v0
	s_nop 1
	v_cndmask_b32_e32 v0, v0, v1, vcc
	v_rsq_f32_e32 v0, v0
	s_nop 0
	v_mul_f32_e32 v1, 0x45800000, v0
	v_cndmask_b32_e32 v0, v0, v1, vcc
	v_lshl_add_u32 v1, v3, 2, v234
	ds_write_b32 v1, v0
	s_branch .LBB0_1243
